# bundle20 + de-serialised load ladders (lever 2): P4 epilogue row-scale loads issued together; P0 rmsnorm loop loads the loop-invariant gain once instead of 8 serialized loads per row
# speedup vs baseline: 1.0089x; 1.0026x over previous
.LBB0_222:
	s_movk_i32 s10, 0x7fff
	s_cmpk_gt_i32 s4, 0x7fff
	v_lshlrev_b32_e32 v18, 3, v252
	s_cbranch_scc1 .LBB0_225
	v_mbcnt_lo_u32_b32 v1, -1, 0
	v_mbcnt_hi_u32_b32 v1, -1, v1
	v_and_b32_e32 v4, 64, v1
	v_add_u32_e32 v4, 64, v4
	v_xor_b32_e32 v5, 1, v1
	v_cmp_lt_i32_e32 vcc, v5, v4
	s_ashr_i32 s5, s4, 31
	s_lshl_b64 s[2:3], s[4:5], 12
	v_cndmask_b32_e32 v5, v1, v5, vcc
	v_lshlrev_b32_e32 v35, 2, v5
	v_xor_b32_e32 v5, 2, v1
	v_cmp_lt_i32_e32 vcc, v5, v4
	v_mov_b32_e32 v3, 0
	s_add_u32 s2, s26, s2
	v_cndmask_b32_e32 v5, v1, v5, vcc
	v_lshlrev_b32_e32 v36, 2, v5
	v_xor_b32_e32 v5, 4, v1
	v_cmp_lt_i32_e32 vcc, v5, v4
	v_mov_b32_e32 v19, v3
	s_addc_u32 s3, s27, s3
	v_cndmask_b32_e32 v5, v1, v5, vcc
	v_lshlrev_b32_e32 v37, 2, v5
	v_xor_b32_e32 v5, 8, v1
	v_cmp_lt_i32_e32 vcc, v5, v4
	v_lshlrev_b32_e32 v2, 4, v252
	s_ashr_i32 s7, s6, 31
	v_cndmask_b32_e32 v5, v1, v5, vcc
	v_lshlrev_b32_e32 v38, 2, v5
	v_xor_b32_e32 v5, 16, v1
	v_cmp_lt_i32_e32 vcc, v5, v4
	v_lshl_add_u64 v[20:21], s[72:73], 0, v[2:3]
	s_mov_b64 s[0:1], 0x1000
	v_cndmask_b32_e32 v5, v1, v5, vcc
	v_lshlrev_b32_e32 v39, 2, v5
	v_xor_b32_e32 v5, 32, v1
	v_cmp_lt_i32_e32 vcc, v5, v4
	s_lshl_b64 s[8:9], s[4:5], 13
	v_lshl_add_u64 v[22:23], v[20:21], 0, s[0:1]
	v_cndmask_b32_e32 v1, v1, v5, vcc
	v_lshl_add_u64 v[4:5], s[2:3], 0, v[18:19]
	s_mov_b64 s[2:3], 0x8000e00
	v_lshl_add_u64 v[30:31], v[4:5], 0, s[2:3]
	s_lshl_b64 s[2:3], s[6:7], 12
	s_mov_b64 s[0:1], 0x1400
	s_add_u32 s8, s68, s8
	v_lshl_add_u64 v[24:25], v[20:21], 0, s[0:1]
	s_mov_b64 s[0:1], 0x1800
	s_addc_u32 s9, s69, s9
	v_lshl_add_u64 v[26:27], v[20:21], 0, s[0:1]
	s_mov_b64 s[0:1], 0x1c00
	v_lshl_add_u64 v[2:3], s[8:9], 0, v[2:3]
	v_lshlrev_b32_e32 v40, 2, v1
	v_lshl_add_u64 v[28:29], v[20:21], 0, s[0:1]
	v_lshl_add_u64 v[32:33], v[2:3], 0, s[0:1]
	s_lshl_b64 s[8:9], s[6:7], 13
	v_mov_b32_e32 v19, 0x358637bd
	s_mov_b32 s5, 0xf800000
	v_mov_b32_e32 v41, 0x260
	v_mov_b32_e32 v42, 1
	s_mov_b32 s7, s4
	global_load_dwordx4 v[200:203], v[20:21], off
	global_load_dwordx4 v[204:207], v[20:21], off offset:1024
	global_load_dwordx4 v[208:211], v[20:21], off offset:2048
	global_load_dwordx4 v[212:215], v[20:21], off offset:3072
	global_load_dwordx4 v[216:219], v[22:23], off
	global_load_dwordx4 v[220:223], v[24:25], off
	global_load_dwordx4 v[224:227], v[26:27], off
	global_load_dwordx4 v[228:231], v[28:29], off
	s_waitcnt vmcnt(0)
.LBB0_224:
	global_load_dwordx4 v[14:17], v[32:33], off offset:-3072
	global_load_dwordx4 v[10:13], v[32:33], off offset:-2048
	global_load_dwordx4 v[2:5], v[32:33], off
	global_load_dwordx4 v[6:9], v[32:33], off offset:-1024
	v_add_co_u32_e32 v56, vcc, 0xfffff000, v32
	s_add_i32 s7, s7, s6
	s_nop 0
	v_addc_co_u32_e32 v57, vcc, -1, v33, vcc
	global_load_dwordx4 v[48:51], v[56:57], off offset:-3072
	global_load_dwordx4 v[52:55], v[56:57], off offset:-2048
	s_nop 0
	global_load_dwordx4 v[56:59], v[56:57], off offset:-1024
	s_nop 0
	global_load_dwordx4 v[60:63], v[32:33], off offset:-4096
	s_cmpk_gt_i32 s7, 0x7fff
	v_lshl_add_u64 v[32:33], v[32:33], 0, s[8:9]
	s_nop 0
	s_waitcnt vmcnt(7)
	v_mul_f32_e32 v1, v14, v14
	s_nop 0
	s_waitcnt vmcnt(6)
	v_pk_mul_f32 v[64:65], v[12:13], v[12:13]
	v_pk_mul_f32 v[66:67], v[10:11], v[10:11]
	s_nop 0
	s_waitcnt vmcnt(4)
	v_mul_f32_e32 v34, v7, v7
	v_mul_f32_e32 v68, v9, v9
	v_mul_f32_e32 v85, v4, v4
	v_mul_f32_e32 v90, v5, v5
	s_nop 0
	v_mov_b32_e32 v70, v200
	v_mov_b32_e32 v71, v202
	v_mov_b32_e32 v46, v201
	v_pk_mov_b32 v[44:45], v[66:67], v[64:65] op_sel:[1,0]
	v_mov_b32_e32 v67, v65
	v_pk_fma_f32 v[64:65], v[6:7], v[6:7], v[34:35] op_sel_hi:[1,1,0]
	v_pk_fma_f32 v[68:69], v[8:9], v[8:9], v[68:69] op_sel_hi:[1,1,0]
	s_nop 0
	s_waitcnt vmcnt(3)
	v_mov_b32_e32 v74, v49
	s_nop 0
	s_waitcnt vmcnt(2)
	v_mov_b32_e32 v75, v53
	v_mov_b32_e32 v78, v51
	v_mov_b32_e32 v79, v55
	v_mov_b32_e32 v72, v48
	v_mov_b32_e32 v73, v52
	v_mov_b32_e32 v76, v50
	v_mov_b32_e32 v77, v54
	s_nop 0
	s_waitcnt vmcnt(1)
	v_pk_mul_f32 v[80:81], v[58:59], v[58:59]
	v_pk_mul_f32 v[82:83], v[56:57], v[56:57]
	v_pk_add_f32 v[44:45], v[44:45], v[66:67]
	v_mov_b32_e32 v65, v85
	v_mov_b32_e32 v69, v90
	v_mov_b32_e32 v66, v48
	v_mov_b32_e32 v67, v50
	v_mov_b32_e32 v50, v49
	v_mov_b32_e32 v48, v52
	v_mov_b32_e32 v49, v54
	v_mov_b32_e32 v54, v53
	v_pk_mul_f32 v[52:53], v[74:75], v[74:75]
	v_pk_mul_f32 v[74:75], v[78:79], v[78:79]
	v_pk_mov_b32 v[78:79], v[82:83], v[80:81] op_sel:[1,0]
	v_mov_b32_e32 v83, v81
	v_pk_add_f32 v[64:65], v[64:65], v[68:69]
	v_pk_fma_f32 v[52:53], v[72:73], v[72:73], v[52:53]
	v_pk_fma_f32 v[68:69], v[76:77], v[76:77], v[74:75]
	s_nop 0
	s_waitcnt vmcnt(0)
	v_mul_f32_e32 v34, v61, v61
	v_mul_f32_e32 v84, v63, v63
	v_pk_add_f32 v[72:73], v[78:79], v[82:83]
	v_pk_add_f32 v[52:53], v[52:53], v[68:69]
	v_mul_f32_e32 v43, v15, v15
	v_mul_f32_e32 v86, v16, v16
	v_mul_f32_e32 v87, v17, v17
	v_pk_fma_f32 v[80:81], v[60:61], v[60:61], v[34:35] op_sel_hi:[1,1,0]
	v_pk_fma_f32 v[84:85], v[62:63], v[62:63], v[84:85] op_sel_hi:[1,1,0]
	v_pk_add_f32 v[68:69], v[72:73], v[72:73] op_sel:[0,1] op_sel_hi:[1,0]
	v_pk_add_f32 v[52:53], v[52:53], v[52:53] op_sel:[0,1] op_sel_hi:[1,0]
	v_mov_b32_e32 v81, v86
	v_mov_b32_e32 v85, v87
	v_mov_b32_e32 v69, v43
	v_mov_b32_e32 v53, v1
	v_pk_add_f32 v[72:73], v[80:81], v[84:85]
	v_pk_add_f32 v[52:53], v[52:53], v[68:69]
	v_mul_f32_e32 v88, v2, v2
	v_pk_add_f32 v[52:53], v[52:53], v[72:73]
	v_mul_f32_e32 v89, v3, v3
	v_pk_add_f32 v[44:45], v[44:45], v[44:45] op_sel:[0,1] op_sel_hi:[1,0]
	v_pk_add_f32 v[52:53], v[52:53], v[52:53] op_sel:[0,1] op_sel_hi:[1,0]
	v_mov_b32_e32 v45, v89
	v_mov_b32_e32 v53, v88
	v_pk_add_f32 v[44:45], v[52:53], v[44:45]
	s_nop 0
	v_pk_add_f32 v[44:45], v[44:45], v[64:65]
	s_nop 0
	v_add_f32_e32 v1, v44, v45
	ds_bpermute_b32 v34, v35, v1
	s_waitcnt lgkmcnt(0)
	v_add_f32_e32 v1, v1, v34
	ds_bpermute_b32 v34, v36, v1
	s_waitcnt lgkmcnt(0)
	v_add_f32_e32 v1, v1, v34
	ds_bpermute_b32 v34, v37, v1
	s_waitcnt lgkmcnt(0)
	v_add_f32_e32 v1, v1, v34
	ds_bpermute_b32 v34, v38, v1
	s_waitcnt lgkmcnt(0)
	v_add_f32_e32 v1, v1, v34
	ds_bpermute_b32 v34, v39, v1
	s_waitcnt lgkmcnt(0)
	v_add_f32_e32 v1, v1, v34
	ds_bpermute_b32 v34, v40, v1
	s_waitcnt lgkmcnt(0)
	v_add_f32_e32 v1, v1, v34
	v_fmamk_f32 v1, v1, 0x3a000000, v19
	v_mul_f32_e32 v34, 0x4f800000, v1
	v_cmp_gt_f32_e32 vcc, s5, v1
	s_nop 1
	v_cndmask_b32_e32 v1, v1, v34, vcc
	v_sqrt_f32_e32 v34, v1
	s_nop 0
	v_add_u32_e32 v43, -1, v34
	v_add_u32_e32 v44, 1, v34
	v_fma_f32 v45, -v43, v34, v1
	v_fma_f32 v52, -v44, v34, v1
	v_cmp_ge_f32_e64 s[0:1], 0, v45
	s_nop 1
	v_cndmask_b32_e64 v34, v34, v43, s[0:1]
	v_cmp_lt_f32_e64 s[0:1], 0, v52
	s_nop 1
	v_cndmask_b32_e64 v34, v34, v44, s[0:1]
	v_mul_f32_e32 v43, 0x37800000, v34
	v_cndmask_b32_e32 v34, v34, v43, vcc
	v_cmp_class_f32_e32 vcc, v1, v41
	s_nop 1
	v_cndmask_b32_e32 v1, v34, v1, vcc
	v_div_scale_f32 v34, s[0:1], v1, v1, 1.0
	v_rcp_f32_e32 v44, v34
	v_div_scale_f32 v43, vcc, 1.0, v1, 1.0
	v_fma_f32 v45, -v34, v44, 1.0
	v_fmac_f32_e32 v44, v45, v44
	v_mul_f32_e32 v45, v43, v44
	v_fma_f32 v52, -v34, v45, v43
	v_fmac_f32_e32 v45, v52, v44
	v_fma_f32 v34, -v34, v45, v43
	v_div_fmas_f32 v34, v34, v44, v45
	v_div_fixup_f32 v34, v34, v1, 1.0
	v_pk_mul_f32 v[44:45], v[66:67], v[34:35] op_sel_hi:[1,0]
	v_pk_mul_f32 v[50:51], v[50:51], v[34:35] op_sel_hi:[1,0]
	v_pk_mul_f32 v[44:45], v[70:71], v[44:45]
	v_mov_b32_e32 v47, v203
	v_pk_mul_f32 v[46:47], v[46:47], v[50:51]
	v_and_b32_sdwa v1, v45, v42 dst_sel:DWORD dst_unused:UNUSED_PAD src0_sel:WORD_1 src1_sel:DWORD
	v_and_b32_sdwa v43, v44, v42 dst_sel:DWORD dst_unused:UNUSED_PAD src0_sel:WORD_1 src1_sel:DWORD
	v_and_b32_sdwa v50, v47, v42 dst_sel:DWORD dst_unused:UNUSED_PAD src0_sel:WORD_1 src1_sel:DWORD
	v_and_b32_sdwa v51, v46, v42 dst_sel:DWORD dst_unused:UNUSED_PAD src0_sel:WORD_1 src1_sel:DWORD
	v_add3_u32 v43, v44, v43, s10
	v_add3_u32 v1, v45, v1, s10
	v_add3_u32 v44, v47, v50, s10
	v_add3_u32 v45, v46, v51, s10
	v_and_b32_e32 v44, 0xffff0000, v44
	v_and_b32_e32 v46, 0xffff0000, v45
	v_or_b32_sdwa v45, v44, v1 dst_sel:DWORD dst_unused:UNUSED_PAD src0_sel:DWORD src1_sel:WORD_1
	v_or_b32_sdwa v44, v46, v43 dst_sel:DWORD dst_unused:UNUSED_PAD src0_sel:DWORD src1_sel:WORD_1
	global_store_dwordx2 v[30:31], v[44:45], off offset:-3584
	v_pk_mul_f32 v[48:49], v[48:49], v[34:35] op_sel_hi:[1,0]
	v_pk_mul_f32 v[50:51], v[54:55], v[34:35] op_sel_hi:[1,0]
	s_nop 0
	v_mov_b32_e32 v52, v204
	v_mov_b32_e32 v53, v206
	v_mov_b32_e32 v46, v205
	v_pk_mul_f32 v[44:45], v[52:53], v[48:49]
	v_mov_b32_e32 v47, v207
	v_pk_mul_f32 v[46:47], v[46:47], v[50:51]
	v_and_b32_sdwa v1, v45, v42 dst_sel:DWORD dst_unused:UNUSED_PAD src0_sel:WORD_1 src1_sel:DWORD
	v_and_b32_sdwa v43, v44, v42 dst_sel:DWORD dst_unused:UNUSED_PAD src0_sel:WORD_1 src1_sel:DWORD
	v_and_b32_sdwa v48, v47, v42 dst_sel:DWORD dst_unused:UNUSED_PAD src0_sel:WORD_1 src1_sel:DWORD
	v_and_b32_sdwa v49, v46, v42 dst_sel:DWORD dst_unused:UNUSED_PAD src0_sel:WORD_1 src1_sel:DWORD
	v_add3_u32 v43, v44, v43, s10
	v_add3_u32 v1, v45, v1, s10
	v_add3_u32 v44, v47, v48, s10
	v_add3_u32 v45, v46, v49, s10
	v_and_b32_e32 v44, 0xffff0000, v44
	v_and_b32_e32 v46, 0xffff0000, v45
	v_or_b32_sdwa v45, v44, v1 dst_sel:DWORD dst_unused:UNUSED_PAD src0_sel:DWORD src1_sel:WORD_1
	v_or_b32_sdwa v44, v46, v43 dst_sel:DWORD dst_unused:UNUSED_PAD src0_sel:DWORD src1_sel:WORD_1
	global_store_dwordx2 v[30:31], v[44:45], off offset:-3072
	v_mov_b32_e32 v48, v56
	v_mov_b32_e32 v49, v58
	v_mov_b32_e32 v58, v57
	v_pk_mul_f32 v[48:49], v[48:49], v[34:35] op_sel_hi:[1,0]
	v_pk_mul_f32 v[50:51], v[58:59], v[34:35] op_sel_hi:[1,0]
	s_nop 0
	v_mov_b32_e32 v52, v208
	v_mov_b32_e32 v53, v210
	v_mov_b32_e32 v46, v209
	v_pk_mul_f32 v[44:45], v[52:53], v[48:49]
	v_mov_b32_e32 v47, v211
	v_pk_mul_f32 v[46:47], v[46:47], v[50:51]
	v_and_b32_sdwa v1, v45, v42 dst_sel:DWORD dst_unused:UNUSED_PAD src0_sel:WORD_1 src1_sel:DWORD
	v_and_b32_sdwa v43, v44, v42 dst_sel:DWORD dst_unused:UNUSED_PAD src0_sel:WORD_1 src1_sel:DWORD
	v_and_b32_sdwa v48, v47, v42 dst_sel:DWORD dst_unused:UNUSED_PAD src0_sel:WORD_1 src1_sel:DWORD
	v_and_b32_sdwa v49, v46, v42 dst_sel:DWORD dst_unused:UNUSED_PAD src0_sel:WORD_1 src1_sel:DWORD
	v_add3_u32 v43, v44, v43, s10
	v_add3_u32 v1, v45, v1, s10
	v_add3_u32 v44, v47, v48, s10
	v_add3_u32 v45, v46, v49, s10
	v_and_b32_e32 v44, 0xffff0000, v44
	v_and_b32_e32 v46, 0xffff0000, v45
	v_or_b32_sdwa v45, v44, v1 dst_sel:DWORD dst_unused:UNUSED_PAD src0_sel:DWORD src1_sel:WORD_1
	v_or_b32_sdwa v44, v46, v43 dst_sel:DWORD dst_unused:UNUSED_PAD src0_sel:DWORD src1_sel:WORD_1
	global_store_dwordx2 v[30:31], v[44:45], off offset:-2560
	v_mov_b32_e32 v48, v60
	v_mov_b32_e32 v49, v62
	v_mov_b32_e32 v62, v61
	v_pk_mul_f32 v[48:49], v[48:49], v[34:35] op_sel_hi:[1,0]
	v_pk_mul_f32 v[50:51], v[62:63], v[34:35] op_sel_hi:[1,0]
	s_nop 0
	v_mov_b32_e32 v52, v212
	v_mov_b32_e32 v53, v214
	v_mov_b32_e32 v46, v213
	v_pk_mul_f32 v[44:45], v[48:49], v[52:53]
	v_mov_b32_e32 v47, v215
	v_pk_mul_f32 v[46:47], v[50:51], v[46:47]
	v_and_b32_sdwa v1, v45, v42 dst_sel:DWORD dst_unused:UNUSED_PAD src0_sel:WORD_1 src1_sel:DWORD
	v_and_b32_sdwa v43, v44, v42 dst_sel:DWORD dst_unused:UNUSED_PAD src0_sel:WORD_1 src1_sel:DWORD
	v_and_b32_sdwa v48, v47, v42 dst_sel:DWORD dst_unused:UNUSED_PAD src0_sel:WORD_1 src1_sel:DWORD
	v_and_b32_sdwa v49, v46, v42 dst_sel:DWORD dst_unused:UNUSED_PAD src0_sel:WORD_1 src1_sel:DWORD
	v_add3_u32 v43, v44, v43, s10
	v_add3_u32 v1, v45, v1, s10
	v_add3_u32 v44, v47, v48, s10
	v_add3_u32 v45, v46, v49, s10
	v_and_b32_e32 v44, 0xffff0000, v44
	v_and_b32_e32 v46, 0xffff0000, v45
	v_or_b32_sdwa v45, v44, v1 dst_sel:DWORD dst_unused:UNUSED_PAD src0_sel:DWORD src1_sel:WORD_1
	v_or_b32_sdwa v44, v46, v43 dst_sel:DWORD dst_unused:UNUSED_PAD src0_sel:DWORD src1_sel:WORD_1
	global_store_dwordx2 v[30:31], v[44:45], off offset:-2048
	v_mov_b32_e32 v48, v14
	v_mov_b32_e32 v49, v16
	v_mov_b32_e32 v16, v15
	v_pk_mul_f32 v[14:15], v[48:49], v[34:35] op_sel_hi:[1,0]
	v_pk_mul_f32 v[16:17], v[16:17], v[34:35] op_sel_hi:[1,0]
	s_nop 0
	v_mov_b32_e32 v48, v216
	v_mov_b32_e32 v49, v218
	v_mov_b32_e32 v46, v217
	v_pk_mul_f32 v[14:15], v[14:15], v[48:49]
	v_mov_b32_e32 v47, v219
	v_pk_mul_f32 v[16:17], v[16:17], v[46:47]
	v_and_b32_sdwa v1, v15, v42 dst_sel:DWORD dst_unused:UNUSED_PAD src0_sel:WORD_1 src1_sel:DWORD
	v_and_b32_sdwa v44, v17, v42 dst_sel:DWORD dst_unused:UNUSED_PAD src0_sel:WORD_1 src1_sel:DWORD
	v_and_b32_sdwa v45, v16, v42 dst_sel:DWORD dst_unused:UNUSED_PAD src0_sel:WORD_1 src1_sel:DWORD
	v_and_b32_sdwa v43, v14, v42 dst_sel:DWORD dst_unused:UNUSED_PAD src0_sel:WORD_1 src1_sel:DWORD
	v_add3_u32 v1, v15, v1, s10
	v_add3_u32 v15, v17, v44, s10
	v_add3_u32 v16, v16, v45, s10
	v_add3_u32 v14, v14, v43, s10
	v_and_b32_e32 v15, 0xffff0000, v15
	v_and_b32_e32 v16, 0xffff0000, v16
	v_or_b32_sdwa v15, v15, v1 dst_sel:DWORD dst_unused:UNUSED_PAD src0_sel:DWORD src1_sel:WORD_1
	v_or_b32_sdwa v14, v16, v14 dst_sel:DWORD dst_unused:UNUSED_PAD src0_sel:DWORD src1_sel:WORD_1
	global_store_dwordx2 v[30:31], v[14:15], off offset:-1536
	v_mov_b32_e32 v44, v10
	v_mov_b32_e32 v45, v12
	v_mov_b32_e32 v12, v11
	v_pk_mul_f32 v[10:11], v[44:45], v[34:35] op_sel_hi:[1,0]
	v_pk_mul_f32 v[12:13], v[12:13], v[34:35] op_sel_hi:[1,0]
	s_nop 0
	v_mov_b32_e32 v44, v220
	v_mov_b32_e32 v45, v222
	v_mov_b32_e32 v16, v221
	v_pk_mul_f32 v[10:11], v[10:11], v[44:45]
	v_mov_b32_e32 v17, v223
	v_pk_mul_f32 v[12:13], v[12:13], v[16:17]
	v_and_b32_sdwa v1, v11, v42 dst_sel:DWORD dst_unused:UNUSED_PAD src0_sel:WORD_1 src1_sel:DWORD
	v_and_b32_sdwa v15, v13, v42 dst_sel:DWORD dst_unused:UNUSED_PAD src0_sel:WORD_1 src1_sel:DWORD
	v_and_b32_sdwa v16, v12, v42 dst_sel:DWORD dst_unused:UNUSED_PAD src0_sel:WORD_1 src1_sel:DWORD
	v_and_b32_sdwa v14, v10, v42 dst_sel:DWORD dst_unused:UNUSED_PAD src0_sel:WORD_1 src1_sel:DWORD
	v_add3_u32 v1, v11, v1, s10
	v_add3_u32 v11, v13, v15, s10
	v_add3_u32 v12, v12, v16, s10
	v_add3_u32 v10, v10, v14, s10
	v_and_b32_e32 v11, 0xffff0000, v11
	v_and_b32_e32 v12, 0xffff0000, v12
	v_or_b32_sdwa v11, v11, v1 dst_sel:DWORD dst_unused:UNUSED_PAD src0_sel:DWORD src1_sel:WORD_1
	v_or_b32_sdwa v10, v12, v10 dst_sel:DWORD dst_unused:UNUSED_PAD src0_sel:DWORD src1_sel:WORD_1
	global_store_dwordx2 v[30:31], v[10:11], off offset:-1024
	v_mov_b32_e32 v14, v6
	v_mov_b32_e32 v15, v8
	v_mov_b32_e32 v8, v7
	v_pk_mul_f32 v[6:7], v[14:15], v[34:35] op_sel_hi:[1,0]
	v_pk_mul_f32 v[8:9], v[8:9], v[34:35] op_sel_hi:[1,0]
	s_nop 0
	v_mov_b32_e32 v14, v224
	v_mov_b32_e32 v15, v226
	v_mov_b32_e32 v12, v225
	v_pk_mul_f32 v[6:7], v[6:7], v[14:15]
	v_mov_b32_e32 v13, v227
	v_pk_mul_f32 v[8:9], v[8:9], v[12:13]
	v_and_b32_sdwa v1, v7, v42 dst_sel:DWORD dst_unused:UNUSED_PAD src0_sel:WORD_1 src1_sel:DWORD
	v_and_b32_sdwa v11, v9, v42 dst_sel:DWORD dst_unused:UNUSED_PAD src0_sel:WORD_1 src1_sel:DWORD
	v_and_b32_sdwa v12, v8, v42 dst_sel:DWORD dst_unused:UNUSED_PAD src0_sel:WORD_1 src1_sel:DWORD
	v_and_b32_sdwa v10, v6, v42 dst_sel:DWORD dst_unused:UNUSED_PAD src0_sel:WORD_1 src1_sel:DWORD
	v_add3_u32 v1, v7, v1, s10
	v_add3_u32 v7, v9, v11, s10
	v_add3_u32 v8, v8, v12, s10
	v_add3_u32 v6, v6, v10, s10
	v_and_b32_e32 v7, 0xffff0000, v7
	v_and_b32_e32 v8, 0xffff0000, v8
	v_or_b32_sdwa v7, v7, v1 dst_sel:DWORD dst_unused:UNUSED_PAD src0_sel:DWORD src1_sel:WORD_1
	v_or_b32_sdwa v6, v8, v6 dst_sel:DWORD dst_unused:UNUSED_PAD src0_sel:DWORD src1_sel:WORD_1
	global_store_dwordx2 v[30:31], v[6:7], off offset:-512
	v_mov_b32_e32 v10, v2
	v_mov_b32_e32 v11, v4
	v_mov_b32_e32 v4, v3
	v_pk_mul_f32 v[2:3], v[10:11], v[34:35] op_sel_hi:[1,0]
	v_pk_mul_f32 v[4:5], v[4:5], v[34:35] op_sel_hi:[1,0]
	s_nop 0
	v_mov_b32_e32 v10, v228
	v_mov_b32_e32 v11, v230
	v_mov_b32_e32 v8, v229
	v_pk_mul_f32 v[2:3], v[2:3], v[10:11]
	v_mov_b32_e32 v9, v231
	v_pk_mul_f32 v[4:5], v[4:5], v[8:9]
	v_and_b32_sdwa v1, v3, v42 dst_sel:DWORD dst_unused:UNUSED_PAD src0_sel:WORD_1 src1_sel:DWORD
	v_and_b32_sdwa v7, v5, v42 dst_sel:DWORD dst_unused:UNUSED_PAD src0_sel:WORD_1 src1_sel:DWORD
	v_and_b32_sdwa v8, v4, v42 dst_sel:DWORD dst_unused:UNUSED_PAD src0_sel:WORD_1 src1_sel:DWORD
	v_and_b32_sdwa v6, v2, v42 dst_sel:DWORD dst_unused:UNUSED_PAD src0_sel:WORD_1 src1_sel:DWORD
	v_add3_u32 v1, v3, v1, s10
	v_add3_u32 v3, v5, v7, s10
	v_add3_u32 v4, v4, v8, s10
	v_add3_u32 v2, v2, v6, s10
	v_and_b32_e32 v3, 0xffff0000, v3
	v_and_b32_e32 v4, 0xffff0000, v4
	v_or_b32_sdwa v3, v3, v1 dst_sel:DWORD dst_unused:UNUSED_PAD src0_sel:DWORD src1_sel:WORD_1
	v_or_b32_sdwa v2, v4, v2 dst_sel:DWORD dst_unused:UNUSED_PAD src0_sel:DWORD src1_sel:WORD_1
	global_store_dwordx2 v[30:31], v[2:3], off
	v_lshl_add_u64 v[30:31], v[30:31], 0, s[2:3]
	s_cbranch_scc0 .LBB0_224

.LBB0_476:
	v_ashrrev_i32_e32 v171, 31, v170
	v_lshl_add_u64 v[50:51], v[170:171], 2, s[26:27]
	global_load_dword v1, v[50:51], off
	global_load_dword v246, v[50:51], off offset:64
	global_load_dword v247, v[50:51], off offset:128
	global_load_dword v248, v[50:51], off offset:192
	global_load_dword v249, v[50:51], off offset:512
	global_load_dword v250, v[50:51], off offset:576
	global_load_dword v251, v[50:51], off offset:640
	global_load_dword v253, v[50:51], off offset:704
	s_waitcnt vmcnt(7)
	v_fmamk_f32 v1, v1, 0x3a000000, v207
	v_cmp_gt_f32_e32 vcc, s55, v1
	v_mul_f32_e32 v52, 0x4f800000, v1
	s_nop 0
	v_cndmask_b32_e32 v1, v1, v52, vcc
	v_sqrt_f32_e32 v52, v1
	s_nop 0
	v_add_u32_e32 v53, -1, v52
	v_fma_f32 v78, -v53, v52, v1
	v_cmp_ge_f32_e64 s[0:1], 0, v78
	v_add_u32_e32 v78, 1, v52
	s_nop 0
	v_cndmask_b32_e64 v53, v52, v53, s[0:1]
	v_fma_f32 v52, -v78, v52, v1
	v_cmp_lt_f32_e64 s[0:1], 0, v52
	s_nop 1
	v_cndmask_b32_e64 v52, v53, v78, s[0:1]
	v_mul_f32_e32 v53, 0x37800000, v52
	v_cndmask_b32_e32 v52, v52, v53, vcc
	v_cmp_class_f32_e32 vcc, v1, v208
	s_nop 1
	v_cndmask_b32_e32 v1, v52, v1, vcc
	s_waitcnt vmcnt(6)
	v_fmamk_f32 v52, v246, 0x3a000000, v207
	v_cmp_gt_f32_e32 vcc, s55, v52
	v_mul_f32_e32 v53, 0x4f800000, v52
	s_nop 0
	v_cndmask_b32_e32 v52, v52, v53, vcc
	v_sqrt_f32_e32 v53, v52
	s_nop 0
	v_add_u32_e32 v78, -1, v53
	v_fma_f32 v79, -v78, v53, v52
	v_cmp_ge_f32_e64 s[0:1], 0, v79
	v_add_u32_e32 v79, 1, v53
	s_nop 0
	v_cndmask_b32_e64 v78, v53, v78, s[0:1]
	v_fma_f32 v53, -v79, v53, v52
	v_cmp_lt_f32_e64 s[0:1], 0, v53
	s_nop 1
	v_cndmask_b32_e64 v53, v78, v79, s[0:1]
	v_mul_f32_e32 v78, 0x37800000, v53
	v_cndmask_b32_e32 v53, v53, v78, vcc
	v_cmp_class_f32_e32 vcc, v52, v208
	s_nop 1
	v_cndmask_b32_e32 v52, v53, v52, vcc
	v_div_scale_f32 v53, s[0:1], v52, v52, 1.0
	v_rcp_f32_e32 v78, v53
	s_nop 0
	v_fma_f32 v79, -v53, v78, 1.0
	v_fmac_f32_e32 v78, v79, v78
	v_div_scale_f32 v79, vcc, 1.0, v52, 1.0
	v_mul_f32_e32 v80, v79, v78
	v_fma_f32 v81, -v53, v80, v79
	v_fmac_f32_e32 v80, v81, v78
	v_fma_f32 v53, -v53, v80, v79
	v_div_fmas_f32 v53, v53, v78, v80
	v_div_fixup_f32 v167, v53, v52, 1.0
	v_div_scale_f32 v52, s[0:1], v1, v1, 1.0
	v_rcp_f32_e32 v53, v52
	s_nop 0
	v_fma_f32 v78, -v52, v53, 1.0
	v_fmac_f32_e32 v53, v78, v53
	v_div_scale_f32 v78, vcc, 1.0, v1, 1.0
	v_mul_f32_e32 v79, v78, v53
	v_fma_f32 v80, -v52, v79, v78
	v_fmac_f32_e32 v79, v80, v53
	v_fma_f32 v52, -v52, v79, v78
	v_div_fmas_f32 v52, v52, v53, v79
	v_div_fixup_f32 v166, v52, v1, 1.0
	s_waitcnt vmcnt(5)
	v_fmamk_f32 v1, v247, 0x3a000000, v207
	v_cmp_gt_f32_e32 vcc, s55, v1
	v_mul_f32_e32 v52, 0x4f800000, v1
	s_nop 0
	v_cndmask_b32_e32 v1, v1, v52, vcc
	v_sqrt_f32_e32 v52, v1
	s_nop 0
	v_add_u32_e32 v53, -1, v52
	v_fma_f32 v78, -v53, v52, v1
	v_cmp_ge_f32_e64 s[0:1], 0, v78
	v_add_u32_e32 v78, 1, v52
	s_nop 0
	v_cndmask_b32_e64 v53, v52, v53, s[0:1]
	v_fma_f32 v52, -v78, v52, v1
	v_cmp_lt_f32_e64 s[0:1], 0, v52
	s_nop 1
	v_cndmask_b32_e64 v52, v53, v78, s[0:1]
	v_mul_f32_e32 v53, 0x37800000, v52
	v_cndmask_b32_e32 v52, v52, v53, vcc
	v_cmp_class_f32_e32 vcc, v1, v208
	s_nop 1
	v_cndmask_b32_e32 v1, v52, v1, vcc
	s_waitcnt vmcnt(4)
	v_fmamk_f32 v52, v248, 0x3a000000, v207
	v_cmp_gt_f32_e32 vcc, s55, v52
	v_mul_f32_e32 v53, 0x4f800000, v52
	s_nop 0
	v_cndmask_b32_e32 v52, v52, v53, vcc
	v_sqrt_f32_e32 v53, v52
	s_nop 0
	v_add_u32_e32 v78, -1, v53
	v_fma_f32 v79, -v78, v53, v52
	v_cmp_ge_f32_e64 s[0:1], 0, v79
	v_add_u32_e32 v79, 1, v53
	s_nop 0
	v_cndmask_b32_e64 v78, v53, v78, s[0:1]
	v_fma_f32 v53, -v79, v53, v52
	v_cmp_lt_f32_e64 s[0:1], 0, v53
	s_nop 1
	v_cndmask_b32_e64 v53, v78, v79, s[0:1]
	v_mul_f32_e32 v78, 0x37800000, v53
	v_cndmask_b32_e32 v53, v53, v78, vcc
	v_cmp_class_f32_e32 vcc, v52, v208
	s_nop 1
	v_cndmask_b32_e32 v52, v53, v52, vcc
	v_div_scale_f32 v53, s[0:1], v52, v52, 1.0
	v_rcp_f32_e32 v78, v53
	s_nop 0
	v_fma_f32 v79, -v53, v78, 1.0
	v_fmac_f32_e32 v78, v79, v78
	v_div_scale_f32 v79, vcc, 1.0, v52, 1.0
	v_mul_f32_e32 v80, v79, v78
	v_fma_f32 v81, -v53, v80, v79
	v_fmac_f32_e32 v80, v81, v78
	v_fma_f32 v53, -v53, v80, v79
	v_div_fmas_f32 v53, v53, v78, v80
	v_div_fixup_f32 v169, v53, v52, 1.0
	v_div_scale_f32 v52, s[0:1], v1, v1, 1.0
	v_rcp_f32_e32 v53, v52
	s_nop 0
	v_fma_f32 v78, -v52, v53, 1.0
	v_fmac_f32_e32 v53, v78, v53
	v_div_scale_f32 v78, vcc, 1.0, v1, 1.0
	v_mul_f32_e32 v79, v78, v53
	v_fma_f32 v80, -v52, v79, v78
	v_fmac_f32_e32 v79, v80, v53
	v_fma_f32 v52, -v52, v79, v78
	v_div_fmas_f32 v52, v52, v53, v79
	v_div_fixup_f32 v168, v52, v1, 1.0
	s_waitcnt vmcnt(3)
	v_fmamk_f32 v1, v249, 0x3a000000, v207
	v_cmp_gt_f32_e32 vcc, s55, v1
	v_mul_f32_e32 v52, 0x4f800000, v1
	s_nop 0
	v_cndmask_b32_e32 v1, v1, v52, vcc
	v_sqrt_f32_e32 v52, v1
	s_nop 0
	v_add_u32_e32 v53, -1, v52
	v_fma_f32 v78, -v53, v52, v1
	v_cmp_ge_f32_e64 s[0:1], 0, v78
	v_add_u32_e32 v78, 1, v52
	s_nop 0
	v_cndmask_b32_e64 v53, v52, v53, s[0:1]
	v_fma_f32 v52, -v78, v52, v1
	v_cmp_lt_f32_e64 s[0:1], 0, v52
	s_nop 1
	v_cndmask_b32_e64 v52, v53, v78, s[0:1]
	v_mul_f32_e32 v53, 0x37800000, v52
	v_cndmask_b32_e32 v52, v52, v53, vcc
	v_cmp_class_f32_e32 vcc, v1, v208
	s_nop 1
	v_cndmask_b32_e32 v1, v52, v1, vcc
	s_waitcnt vmcnt(2)
	v_fmamk_f32 v52, v250, 0x3a000000, v207
	v_cmp_gt_f32_e32 vcc, s55, v52
	v_mul_f32_e32 v53, 0x4f800000, v52
	s_nop 0
	v_cndmask_b32_e32 v52, v52, v53, vcc
	v_sqrt_f32_e32 v53, v52
	s_nop 0
	v_add_u32_e32 v78, -1, v53
	v_fma_f32 v79, -v78, v53, v52
	v_cmp_ge_f32_e64 s[0:1], 0, v79
	v_add_u32_e32 v79, 1, v53
	s_nop 0
	v_cndmask_b32_e64 v78, v53, v78, s[0:1]
	v_fma_f32 v53, -v79, v53, v52
	v_cmp_lt_f32_e64 s[0:1], 0, v53
	s_nop 1
	v_cndmask_b32_e64 v53, v78, v79, s[0:1]
	v_mul_f32_e32 v78, 0x37800000, v53
	v_cndmask_b32_e32 v53, v53, v78, vcc
	v_cmp_class_f32_e32 vcc, v52, v208
	s_nop 1
	v_cndmask_b32_e32 v52, v53, v52, vcc
	v_div_scale_f32 v53, s[0:1], v52, v52, 1.0
	v_rcp_f32_e32 v78, v53
	s_nop 0
	v_fma_f32 v79, -v53, v78, 1.0
	v_fmac_f32_e32 v78, v79, v78
	v_div_scale_f32 v79, vcc, 1.0, v52, 1.0
	v_mul_f32_e32 v80, v79, v78
	v_fma_f32 v81, -v53, v80, v79
	v_fmac_f32_e32 v80, v81, v78
	v_fma_f32 v53, -v53, v80, v79
	v_div_fmas_f32 v53, v53, v78, v80
	v_div_fixup_f32 v79, v53, v52, 1.0
	v_div_scale_f32 v52, s[0:1], v1, v1, 1.0
	v_rcp_f32_e32 v53, v52
	s_nop 0
	v_fma_f32 v78, -v52, v53, 1.0
	v_fmac_f32_e32 v53, v78, v53
	v_div_scale_f32 v78, vcc, 1.0, v1, 1.0
	v_mul_f32_e32 v80, v78, v53
	v_fma_f32 v81, -v52, v80, v78
	v_fmac_f32_e32 v80, v81, v53
	v_fma_f32 v52, -v52, v80, v78
	v_div_fmas_f32 v52, v52, v53, v80
	v_div_fixup_f32 v78, v52, v1, 1.0
	s_waitcnt vmcnt(1)
	v_fmamk_f32 v1, v251, 0x3a000000, v207
	v_cmp_gt_f32_e32 vcc, s55, v1
	v_mul_f32_e32 v52, 0x4f800000, v1
	s_nop 0
	v_cndmask_b32_e32 v1, v1, v52, vcc
	v_sqrt_f32_e32 v52, v1
	s_nop 0
	v_add_u32_e32 v53, -1, v52
	v_fma_f32 v80, -v53, v52, v1
	v_cmp_ge_f32_e64 s[0:1], 0, v80
	v_add_u32_e32 v80, 1, v52
	s_nop 0
	v_cndmask_b32_e64 v53, v52, v53, s[0:1]
	v_fma_f32 v52, -v80, v52, v1
	v_cmp_lt_f32_e64 s[0:1], 0, v52
	s_nop 1
	v_cndmask_b32_e64 v52, v53, v80, s[0:1]
	v_mul_f32_e32 v53, 0x37800000, v52
	v_cndmask_b32_e32 v52, v52, v53, vcc
	v_cmp_class_f32_e32 vcc, v1, v208
	s_nop 1
	v_cndmask_b32_e32 v52, v52, v1, vcc
	s_waitcnt vmcnt(0)
	v_fmamk_f32 v1, v253, 0x3a000000, v207
	v_cmp_gt_f32_e32 vcc, s55, v1
	v_mul_f32_e32 v50, 0x4f800000, v1
	s_nop 0
	v_cndmask_b32_e32 v1, v1, v50, vcc
	v_sqrt_f32_e32 v50, v1
	s_nop 0
	v_add_u32_e32 v51, -1, v50
	v_fma_f32 v53, -v51, v50, v1
	v_cmp_ge_f32_e64 s[0:1], 0, v53
	v_add_u32_e32 v53, 1, v50
	s_nop 0
	v_cndmask_b32_e64 v51, v50, v51, s[0:1]
	v_fma_f32 v50, -v53, v50, v1
	v_cmp_lt_f32_e64 s[0:1], 0, v50
	s_nop 1
	v_cndmask_b32_e64 v50, v51, v53, s[0:1]
	v_mul_f32_e32 v51, 0x37800000, v50
	v_cndmask_b32_e32 v50, v50, v51, vcc
	v_cmp_class_f32_e32 vcc, v1, v208
	s_nop 1
	v_cndmask_b32_e32 v1, v50, v1, vcc
	v_div_scale_f32 v50, s[0:1], v1, v1, 1.0
	v_rcp_f32_e32 v51, v50
	s_nop 0
	v_fma_f32 v53, -v50, v51, 1.0
	v_fmac_f32_e32 v51, v53, v51
	v_div_scale_f32 v53, vcc, 1.0, v1, 1.0
	v_mul_f32_e32 v80, v53, v51
	v_fma_f32 v81, -v50, v80, v53
	v_fmac_f32_e32 v80, v81, v51
	v_fma_f32 v50, -v50, v80, v53
	v_div_fmas_f32 v50, v50, v51, v80
	v_div_fixup_f32 v81, v50, v1, 1.0
	v_div_scale_f32 v1, s[0:1], v52, v52, 1.0
	v_rcp_f32_e32 v50, v1
	s_nop 0
	v_fma_f32 v51, -v1, v50, 1.0
	v_fmac_f32_e32 v50, v51, v50
	v_div_scale_f32 v51, vcc, 1.0, v52, 1.0
	v_mul_f32_e32 v53, v51, v50
	v_fma_f32 v80, -v1, v53, v51
	v_fmac_f32_e32 v53, v80, v50
	v_fma_f32 v1, -v1, v53, v51
	v_div_fmas_f32 v1, v1, v50, v53
	v_div_fixup_f32 v80, v1, v52, 1.0
	v_mov_b32_e32 v50, v78
	v_mov_b32_e32 v51, v79
	v_mov_b32_e32 v52, v80
	v_mov_b32_e32 v53, v81
	s_cmp_lg_u32 s6, 40
	s_mov_b64 s[0:1], -1
	v_and_b32_e32 v252, 63, v0
	s_cbranch_scc0 .LBB0_474
